# HGRN2 chunk loop: gate loads issued before the next chunk's prefetch, output stage waits vmcnt(18) instead of vmcnt(0) (prefetch stays in flight), on top of v24
# speedup vs baseline: 1.0079x; 1.0079x over previous
; __device__ __forceinline__ float bflo(unsigned w) { return __uint_as_float(w << 16); }
; __device__ __forceinline__ float bfhi(unsigned w) { return __uint_as_float(w & 0xffff0000u); }
; __device__ __forceinline__ unsigned f2bf(float f) { unsigned u = __float_as_uint(f); return (u + 0x7fffu + ((u >> 16) & 1u)) >> 16; }
; __device__ __forceinline__ float siluf_(float x) { return x * __builtin_amdgcn_rcpf(1.0f + __expf(-x)); }
; __device__ __forceinline__ int crow(int r, int hi) { return (r & 3) + 8 * (r >> 2) + 4 * hi; }
; __device__ __forceinline__ unsigned cvtpk(float lo, float hi) { unsigned r; asm volatile("v_cvt_pk_bf16_f32 %0, %1, %2" : "=v"(r) : "v"(lo), "v"(hi)); return r; }
; __device__ __forceinline__ int v_st(int k, int c) { const int kk = (k & ~0xC) | ((k & 4) << 1) | ((k & 8) >> 1); return ((kk >> 3) * 4 + (c >> 5)) * 512 + ((kk & 7) * 32 + (c & 31)) * 2; }
; __device__ __forceinline__ void hg_mfma(Frame& F, bf16* Y, int u, unsigned* prog = nullptr) {
;     ...
; #pragma unroll
;       for (int r = 0; r < 16; ++r) { const int d = 32 * dblk + crow(r, hi);
;         *(bf16*)(lds + HG_S + (d >> 6) * 16384 + v_st(d & 63, 32 * vblk0 + r32)) = (bf16)f2bf(Sa[r]);
;         *(bf16*)(lds + HG_S + (d >> 6) * 16384 + v_st(d & 63, 32 * (vblk0 + 1) + r32)) = (bf16)f2bf(Sb[r]); }
;       { const int t = tid >> 3, seg = tid & 7; const size_t row = row0 + (size_t)c * 64 + t;
;         const v4u oa = *(const v4u*)(lds + HG_O + t * 272 + seg * 32), ob = *(const v4u*)(lds + HG_O + t * 272 + seg * 32 + 16);
;         const unsigned ow[8] = {oa.x, oa.y, oa.z, oa.w, ob.x, ob.y, ob.z, ob.w}, gw[8] = {ga.x, ga.y, ga.z, ga.w, gb.x, gb.y, gb.z, gb.w};
;         float ss = 0.f;
; #pragma unroll
;         for (int i = 0; i < 8; ++i) { const float a = bflo(ow[i]), bq = bfhi(ow[i]); ss += a * a + bq * bq; }
;         ss += __shfl_xor(ss, 1); ss += __shfl_xor(ss, 2); ss += __shfl_xor(ss, 4);
;         const float rstd = rsqrtf(ss * (1.f / 128.f) + NORM_EPS);
;         unsigned yw[8]; const float* gnl = (const float*)(lds + HG_GN) + seg * 16;
; #pragma unroll
;         for (int i = 0; i < 8; ++i) { const v2f g2 = *(const v2f*)(gnl + 2 * i); const float gx = g2.x, gy = g2.y;
;           yw[i] = at::cvtpk(bflo(ow[i]) * rstd * gx * siluf_(bflo(gw[i])), bfhi(ow[i]) * rstd * gy * siluf_(bfhi(gw[i]))); }
.LBB0_1784:
	s_or_b64 exec, exec, s[52:53]
	v_bfe_u32 v34, v18, 16, 1
	v_add3_u32 v34, v18, v34, s57
	ds_write_b16_d16_hi v170, v34
	s_nop 3
	v_bfe_u32 v34, v2, 16, 1
	v_add3_u32 v34, v2, v34, s57
	ds_write_b16_d16_hi v171, v34
	v_bfe_u32 v34, v19, 16, 1
	v_add3_u32 v34, v19, v34, s57
	ds_write_b16_d16_hi v170, v34 offset:64
	v_bfe_u32 v34, v3, 16, 1
	v_add3_u32 v34, v3, v34, s57
	ds_write_b16_d16_hi v171, v34 offset:64
	v_bfe_u32 v34, v20, 16, 1
	v_add3_u32 v34, v20, v34, s57
	ds_write_b16_d16_hi v172, v34 offset:128
	v_bfe_u32 v34, v4, 16, 1
	v_add3_u32 v34, v4, v34, s57
	ds_write_b16_d16_hi v173, v34 offset:128
	v_bfe_u32 v34, v21, 16, 1
	v_add3_u32 v34, v21, v34, s57
	ds_write_b16_d16_hi v174, v34 offset:192
	v_bfe_u32 v34, v5, 16, 1
	v_add3_u32 v34, v5, v34, s57
	ds_write_b16_d16_hi v175, v34 offset:192
	v_bfe_u32 v34, v22, 16, 1
	v_add3_u32 v34, v22, v34, s57
	ds_write_b16_d16_hi v176, v34
	v_bfe_u32 v34, v6, 16, 1
	v_add3_u32 v34, v6, v34, s57
	ds_write_b16_d16_hi v177, v34
	v_bfe_u32 v34, v23, 16, 1
	v_add3_u32 v34, v23, v34, s57
	ds_write_b16_d16_hi v178, v34 offset:64
	v_bfe_u32 v34, v7, 16, 1
	v_add3_u32 v34, v7, v34, s57
	ds_write_b16_d16_hi v179, v34 offset:64
	v_bfe_u32 v34, v24, 16, 1
	v_add3_u32 v34, v24, v34, s57
	ds_write_b16_d16_hi v180, v34 offset:128
	v_bfe_u32 v34, v8, 16, 1
	v_add3_u32 v34, v8, v34, s57
	ds_write_b16_d16_hi v181, v34 offset:128
	v_bfe_u32 v34, v25, 16, 1
	v_add3_u32 v34, v25, v34, s57
	ds_write_b16_d16_hi v182, v34 offset:192
	v_bfe_u32 v34, v9, 16, 1
	v_add3_u32 v34, v9, v34, s57
	ds_write_b16_d16_hi v183, v34 offset:192
	v_bfe_u32 v34, v26, 16, 1
	v_add3_u32 v34, v26, v34, s57
	ds_write_b16_d16_hi v184, v34
	v_bfe_u32 v34, v10, 16, 1
	v_add3_u32 v34, v10, v34, s57
	ds_write_b16_d16_hi v185, v34
	v_bfe_u32 v34, v27, 16, 1
	v_add3_u32 v34, v27, v34, s57
	ds_write_b16_d16_hi v186, v34 offset:64
	v_bfe_u32 v34, v11, 16, 1
	v_add3_u32 v34, v11, v34, s57
	ds_write_b16_d16_hi v187, v34 offset:64
	v_bfe_u32 v34, v28, 16, 1
	v_add3_u32 v34, v28, v34, s57
	ds_write_b16_d16_hi v188, v34 offset:128
	v_bfe_u32 v34, v12, 16, 1
	v_add3_u32 v34, v12, v34, s57
	ds_write_b16_d16_hi v189, v34 offset:128
	v_bfe_u32 v34, v29, 16, 1
	v_add3_u32 v34, v29, v34, s57
	ds_write_b16_d16_hi v190, v34 offset:192
	v_bfe_u32 v34, v13, 16, 1
	v_add3_u32 v34, v13, v34, s57
	ds_write_b16_d16_hi v191, v34 offset:192
	v_bfe_u32 v34, v30, 16, 1
	v_add3_u32 v34, v30, v34, s57
	ds_write_b16_d16_hi v192, v34
	v_bfe_u32 v34, v14, 16, 1
	v_add3_u32 v34, v14, v34, s57
	ds_write_b16_d16_hi v193, v34
	v_bfe_u32 v34, v31, 16, 1
	v_add3_u32 v34, v31, v34, s57
	ds_write_b16_d16_hi v194, v34 offset:64
	v_bfe_u32 v34, v15, 16, 1
	v_add3_u32 v34, v15, v34, s57
	ds_write_b16_d16_hi v195, v34 offset:64
	v_bfe_u32 v34, v32, 16, 1
	v_add3_u32 v34, v32, v34, s57
	ds_write_b16_d16_hi v196, v34 offset:128
	v_bfe_u32 v34, v16, 16, 1
	v_add3_u32 v34, v16, v34, s57
	ds_write_b16_d16_hi v197, v34 offset:128
	v_bfe_u32 v34, v33, 16, 1
	v_add3_u32 v34, v33, v34, s57
	ds_write_b16_d16_hi v198, v34 offset:192
	v_bfe_u32 v34, v17, 16, 1
	v_add3_u32 v34, v17, v34, s57
	v_and_b32_e32 v35, 64, v203
	ds_write_b16_d16_hi v199, v34 offset:192
	v_xor_b32_e32 v34, 1, v203
	v_add_u32_e32 v35, 64, v35
	v_cmp_lt_i32_e32 vcc, v34, v35
	s_waitcnt vmcnt(18)
	v_lshlrev_b32_e32 v40, 16, v252
	v_mul_f32_e32 v38, 0xbfb8aa3b, v40
	v_cndmask_b32_e32 v34, v203, v34, vcc
	v_lshlrev_b32_e32 v37, 2, v34
	v_xor_b32_e32 v34, 2, v203
	v_cmp_lt_i32_e32 vcc, v34, v35
	ds_read_b128 v[46:49], v200 offset:16
	v_exp_f32_e32 v42, v38
	v_cndmask_b32_e32 v34, v203, v34, vcc
	v_lshlrev_b32_e32 v45, 2, v34
	v_xor_b32_e32 v34, 4, v203
	v_cmp_lt_i32_e32 vcc, v34, v35
	v_lshlrev_b32_e32 v72, 16, v251
	v_mul_f32_e32 v73, 0xbfb8aa3b, v72
	v_cndmask_b32_e32 v34, v203, v34, vcc
	v_lshlrev_b32_e32 v79, 2, v34
	v_lshlrev_b32_e32 v34, 16, v253
	v_add_f32_e32 v42, 1.0, v42
	v_exp_f32_e32 v74, v73
	v_mul_f32_e32 v35, 0xbfb8aa3b, v34
	s_waitcnt lgkmcnt(0)
	v_and_b32_e32 v39, 0xffff0000, v49
	v_rcp_f32_e32 v44, v42
	v_and_b32_e32 v43, 0xffff0000, v48
	v_and_b32_e32 v42, 0xffff0000, v252
	v_lshlrev_b32_e32 v76, 16, v250
	v_exp_f32_e32 v36, v35
	v_lshlrev_b32_e32 v35, 16, v49
	v_and_b32_e32 v38, 0xffff0000, v253
	v_lshlrev_b32_e32 v41, 16, v48
	v_mul_f32_e32 v48, 0xbfb8aa3b, v42
	v_mov_b32_e32 v64, v39
	v_mov_b32_e32 v65, v43
	v_lshlrev_b32_e32 v73, 16, v47
	v_and_b32_e32 v75, 0xffff0000, v47
	v_mul_f32_e32 v47, 0xbfb8aa3b, v76
	v_exp_f32_e32 v206, v48
	v_mov_b32_e32 v48, v35
	v_mov_b32_e32 v49, v41
	v_pk_mul_f32 v[64:65], v[64:65], v[64:65]
	v_exp_f32_e32 v47, v47
	v_lshlrev_b32_e32 v82, 16, v249
	v_pk_fma_f32 v[48:49], v[48:49], v[48:49], v[64:65]
	v_add_f32_e32 v64, 1.0, v74
	v_and_b32_e32 v74, 0xffff0000, v251
	v_mul_f32_e32 v83, 0xbfb8aa3b, v82
	v_mul_f32_e32 v63, 0xbfb8aa3b, v74
	v_exp_f32_e32 v84, v83
	v_exp_f32_e32 v65, v63
	v_and_b32_e32 v63, 0xffff0000, v46
	v_and_b32_e32 v62, 0xffff0000, v250
	v_lshlrev_b32_e32 v77, 16, v46
	v_add_f32_e32 v47, 1.0, v47
	v_mul_f32_e32 v46, 0xbfb8aa3b, v62
	v_mov_b32_e32 v80, v75
	v_mov_b32_e32 v81, v63
	v_rcp_f32_e32 v78, v47
	v_exp_f32_e32 v207, v46
	v_mov_b32_e32 v46, v73
	v_mov_b32_e32 v47, v77
	v_pk_mul_f32 v[80:81], v[80:81], v[80:81]
	v_lshlrev_b32_e32 v86, 16, v248
	v_pk_fma_f32 v[46:47], v[46:47], v[46:47], v[80:81]
	v_add_f32_e32 v80, 1.0, v84
	v_and_b32_e32 v84, 0xffff0000, v249
	v_mul_f32_e32 v61, 0xbfb8aa3b, v86
	v_exp_f32_e32 v61, v61
	ds_read_b128 v[66:69], v200
	ds_read_b64 v[70:71], v147
	v_and_b32_e32 v60, 0xffff0000, v248
	v_and_b32_e32 v94, 0xffff0000, v246
	v_add_f32_e32 v61, 1.0, v61
	s_waitcnt lgkmcnt(1)
; __device__ __forceinline__ float bflo(unsigned w) { return __uint_as_float(w << 16); }
; __device__ __forceinline__ float bfhi(unsigned w) { return __uint_as_float(w & 0xffff0000u); }
; __device__ __forceinline__ float siluf_(float x) { return x * __builtin_amdgcn_rcpf(1.0f + __expf(-x)); }
; __device__ __forceinline__ unsigned cvtpk(float lo, float hi) { unsigned r; asm volatile("v_cvt_pk_bf16_f32 %0, %1, %2" : "=v"(r) : "v"(lo), "v"(hi)); return r; }
; __device__ __forceinline__ void hg_mfma(Frame& F, bf16* Y, int u, unsigned* prog = nullptr) {
;     ...
;         float ss = 0.f;
; #pragma unroll
;         for (int i = 0; i < 8; ++i) { const float a = bflo(ow[i]), bq = bfhi(ow[i]); ss += a * a + bq * bq; }
;         ss += __shfl_xor(ss, 1); ss += __shfl_xor(ss, 2); ss += __shfl_xor(ss, 4);
;         const float rstd = rsqrtf(ss * (1.f / 128.f) + NORM_EPS);
;         unsigned yw[8]; const float* gnl = (const float*)(lds + HG_GN) + seg * 16;
; #pragma unroll
;         for (int i = 0; i < 8; ++i) { const v2f g2 = *(const v2f*)(gnl + 2 * i); const float gx = g2.x, gy = g2.y;
;           yw[i] = at::cvtpk(bflo(ow[i]) * rstd * gx * siluf_(bflo(gw[i])), bfhi(ow[i]) * rstd * gy * siluf_(bfhi(gw[i]))); }
;         v4u y0, y1; y0.x = yw[0]; y0.y = yw[1]; y0.z = yw[2]; y0.w = yw[3]; y1.x = yw[4]; y1.y = yw[5]; y1.z = yw[6]; y1.w = yw[7];
;         *(v4u*)(Y + row * DM + hd * 128 + seg * 16) = y0; *(v4u*)(Y + row * DM + hd * 128 + seg * 16 + 8) = y1; }
	v_and_b32_e32 v85, 0xffff0000, v69
	v_rcp_f32_e32 v88, v61
	v_and_b32_e32 v61, 0xffff0000, v68
	v_lshlrev_b32_e32 v83, 16, v69
	v_mul_f32_e32 v69, 0xbfb8aa3b, v84
	v_lshlrev_b32_e32 v87, 16, v68
	v_mul_f32_e32 v68, 0xbfb8aa3b, v60
	v_mov_b32_e32 v90, v85
	v_mov_b32_e32 v91, v61
	v_exp_f32_e32 v81, v69
	v_exp_f32_e32 v89, v68
	v_mov_b32_e32 v68, v83
	v_mov_b32_e32 v69, v87
	v_pk_mul_f32 v[90:91], v[90:91], v[90:91]
	v_and_b32_e32 v95, 0xffff0000, v66
	v_pk_fma_f32 v[68:69], v[68:69], v[68:69], v[90:91]
	v_lshlrev_b32_e32 v91, 16, v67
	v_and_b32_e32 v67, 0xffff0000, v67
	v_lshlrev_b32_e32 v93, 16, v66
	v_mov_b32_e32 v204, v95
	v_mov_b32_e32 v205, v67
	v_mov_b32_e32 v96, v93
	v_mov_b32_e32 v97, v91
	v_pk_mul_f32 v[204:205], v[204:205], v[204:205]
	v_lshlrev_b32_e32 v90, 16, v247
	v_pk_fma_f32 v[96:97], v[96:97], v[96:97], v[204:205]
	v_mul_f32_e32 v92, 0xbfb8aa3b, v90
	v_add_f32_e32 v66, v96, v97
	v_add_f32_e32 v66, v69, v66
	v_add_f32_e32 v66, v68, v66
	v_add_f32_e32 v47, v47, v66
	v_add_f32_e32 v46, v46, v47
	v_add_f32_e32 v46, v49, v46
	v_add_f32_e32 v46, v48, v46
	ds_bpermute_b32 v37, v37, v46
	v_exp_f32_e32 v92, v92
	v_and_b32_e32 v66, 0xffff0000, v247
	v_rcp_f32_e32 v80, v80
	v_rcp_f32_e32 v64, v64
	s_waitcnt lgkmcnt(0)
	v_add_f32_e32 v37, v46, v37
	ds_bpermute_b32 v45, v45, v37
	v_add_f32_e32 v47, 1.0, v92
	v_rcp_f32_e32 v48, v47
	v_mul_f32_e32 v47, 0xbfb8aa3b, v66
	v_lshlrev_b32_e32 v92, 16, v246
	s_waitcnt lgkmcnt(0)
	v_add_f32_e32 v37, v37, v45
	ds_bpermute_b32 v45, v79, v37
	v_mul_f32_e32 v46, 0xbfb8aa3b, v92
	v_exp_f32_e32 v49, v47
	v_mul_f32_e32 v47, 0xbfb8aa3b, v94
	v_exp_f32_e32 v46, v46
	s_waitcnt lgkmcnt(0)
	v_add_f32_e32 v37, v37, v45
	v_fmamk_f32 v37, v37, 0x3c000000, v201
	v_exp_f32_e32 v47, v47
	v_mul_f32_e32 v45, 0x4b800000, v37
	v_cmp_gt_f32_e32 vcc, s54, v37
	v_add_f32_e32 v46, 1.0, v46
	v_rcp_f32_e32 v68, v46
	v_cndmask_b32_e32 v37, v37, v45, vcc
	v_rsq_f32_e32 v37, v37
	v_add_f32_e32 v45, 1.0, v47
	v_rcp_f32_e32 v46, v45
	v_add_f32_e32 v36, 1.0, v36
	v_mul_f32_e32 v45, 0x45800000, v37
	v_cndmask_b32_e32 v69, v37, v45, vcc
	v_mov_b32_e32 v47, v69
	v_pk_mul_f32 v[58:59], v[68:69], v[92:93]
	v_pk_mul_f32 v[46:47], v[46:47], v[94:95]
	v_mul_f32_e32 v37, v70, v59
	v_mul_f32_e32 v45, v71, v47
	v_mul_f32_e32 v37, v58, v37
	v_mul_f32_e32 v45, v46, v45
	v_cvt_pk_bf16_f32 v46, v37, v45
	ds_read_b64 v[58:59], v147 offset:8
	v_add_f32_e32 v37, 1.0, v49
	v_rcp_f32_e32 v70, v37
	v_mov_b32_e32 v49, v69
	v_pk_mul_f32 v[48:49], v[48:49], v[90:91]
	v_mov_b32_e32 v71, v69
	s_waitcnt lgkmcnt(0)
	v_mul_f32_e32 v37, v58, v49
	v_mul_f32_e32 v37, v48, v37
	v_pk_mul_f32 v[48:49], v[70:71], v[66:67]
	v_mov_b32_e32 v79, v69
	v_mul_f32_e32 v45, v59, v49
	v_mul_f32_e32 v45, v48, v45
	v_cvt_pk_bf16_f32 v47, v37, v45
	ds_read_b64 v[48:49], v147 offset:16
	v_add_f32_e32 v37, 1.0, v89
	v_rcp_f32_e32 v58, v37
	v_mov_b32_e32 v89, v69
	v_pk_mul_f32 v[66:67], v[88:89], v[86:87]
	v_mov_b32_e32 v59, v69
	s_waitcnt lgkmcnt(0)
	v_mul_f32_e32 v37, v48, v67
	v_pk_mul_f32 v[58:59], v[58:59], v[60:61]
	v_mul_f32_e32 v37, v66, v37
	v_mul_f32_e32 v45, v49, v59
	v_mul_f32_e32 v45, v58, v45
	v_cvt_pk_bf16_f32 v48, v37, v45
	ds_read_b64 v[58:59], v147 offset:24
	v_add_f32_e32 v37, 1.0, v81
	v_rcp_f32_e32 v60, v37
	v_mov_b32_e32 v81, v69
	v_pk_mul_f32 v[66:67], v[80:81], v[82:83]
	v_mov_b32_e32 v61, v69
	s_waitcnt lgkmcnt(0)
	v_mul_f32_e32 v37, v58, v67
	v_pk_mul_f32 v[60:61], v[60:61], v[84:85]
	v_mul_f32_e32 v37, v66, v37
	v_mul_f32_e32 v45, v59, v61
	v_mul_f32_e32 v45, v60, v45
	v_cvt_pk_bf16_f32 v49, v37, v45
	ds_read_b64 v[58:59], v147 offset:32
	v_add_f32_e32 v37, 1.0, v207
	v_rcp_f32_e32 v60, v37
	v_pk_mul_f32 v[66:67], v[78:79], v[76:77]
	v_mov_b32_e32 v61, v69
	s_waitcnt lgkmcnt(0)
	v_mul_f32_e32 v37, v58, v67
	v_pk_mul_f32 v[60:61], v[60:61], v[62:63]
	v_mul_f32_e32 v37, v66, v37
	v_mul_f32_e32 v45, v59, v61
	v_mul_f32_e32 v45, v60, v45
	v_cvt_pk_bf16_f32 v58, v37, v45
	v_add_f32_e32 v37, 1.0, v65
	ds_read_b64 v[60:61], v147 offset:40
	v_rcp_f32_e32 v62, v37
	v_mov_b32_e32 v65, v69
	v_mov_b32_e32 v63, v69
	v_pk_mul_f32 v[64:65], v[64:65], v[72:73]
	v_pk_mul_f32 v[62:63], v[62:63], v[74:75]
	s_waitcnt lgkmcnt(0)
	v_mul_f32_e32 v37, v60, v65
	v_mul_f32_e32 v45, v61, v63
	v_mul_f32_e32 v37, v64, v37
	v_mul_f32_e32 v45, v62, v45
	v_cvt_pk_bf16_f32 v59, v37, v45
	ds_read_b64 v[60:61], v147 offset:48
	v_add_f32_e32 v37, 1.0, v206
	v_rcp_f32_e32 v62, v37
	v_mov_b32_e32 v45, v69
	v_pk_mul_f32 v[40:41], v[44:45], v[40:41]
	v_mov_b32_e32 v63, v69
	s_waitcnt lgkmcnt(0)
	v_mul_f32_e32 v37, v60, v41
	v_mul_f32_e32 v37, v40, v37
	v_pk_mul_f32 v[40:41], v[62:63], v[42:43]
	v_rcp_f32_e32 v36, v36
	v_mul_f32_e32 v41, v61, v41
	v_mul_f32_e32 v40, v40, v41
	v_mul_f32_e32 v41, 0xbfb8aa3b, v38
	v_exp_f32_e32 v42, v41
	v_cvt_pk_bf16_f32 v60, v37, v40
	ds_read_b64 v[40:41], v147 offset:56
	v_mov_b32_e32 v37, v69
	v_add_f32_e32 v42, 1.0, v42
	v_rcp_f32_e32 v68, v42
	v_pk_mul_f32 v[34:35], v[36:37], v[34:35]
	s_add_u32 s72, s72, 0x200000
	s_waitcnt lgkmcnt(0)
	v_mul_f32_e32 v35, v40, v35
	v_mul_f32_e32 v36, v34, v35
	v_pk_mul_f32 v[34:35], v[68:69], v[38:39]
	s_addc_u32 s73, s73, 0
	v_mul_f32_e32 v35, v41, v35
	s_add_i32 s1, s1, 1
	s_mov_b64 s[52:53], 0x80000
	v_mul_f32_e32 v34, v34, v35
	v_cvt_pk_bf16_f32 v61, v36, v34
	global_store_dwordx4 v[106:107], v[46:49], off
	global_store_dwordx4 v[106:107], v[58:61], off offset:16
	s_cmp_lg_u32 s72, 0x4000000
	v_lshl_add_u64 v[106:107], v[106:107], 0, s[52:53]
	s_cbranch_scc0 .LBB0_1798

; __device__ __forceinline__ void hg_mfma(Frame& F, bf16* Y, int u, unsigned* prog = nullptr) {
;     ...
;       if (c + 1 < SEQ / 64) HG_LOAD(c + 1);
;       __syncthreads();
;       { const size_t row_ = row0 + (size_t)c * 64 + (tid >> 3); ga = *(const v4u*)(proj + row_ * HG_NP + 12288 + hd * 128 + (tid & 7) * 16); gb = *(const v4u*)(proj + row_ * HG_NP + 12288 + hd * 128 + (tid & 7) * 16 + 8); }
.LBB0_1787:
	s_mov_b32 s98, 0x24006000
	s_mov_b32 s99, 0
	v_lshl_add_u64 v[246:247], v[108:109], 0, s[72:73]
	v_lshl_add_u64 v[246:247], v[246:247], 0, s[98:99]
	global_load_dwordx4 v[250:253], v[246:247], off offset:16
	global_load_dwordx4 v[246:249], v[246:247], off
	s_cmp_eq_u32 s72, 0x3e00000
	s_cbranch_scc1 .Lmy_hg_last
	v_lshl_add_u64 v[34:35], v[112:113], 0, s[72:73]
	v_add_co_u32_e32 v36, vcc, 0x24200000, v34
	s_nop 1
	v_addc_co_u32_e32 v37, vcc, 0, v35, vcc
	v_add_co_u32_e32 v38, vcc, 0x24202000, v34
	s_nop 1
	v_addc_co_u32_e32 v39, vcc, 0, v35, vcc
	v_add_co_u32_e32 v40, vcc, 0x24208000, v34
	s_nop 1
	v_addc_co_u32_e32 v41, vcc, 0, v35, vcc
	v_add_co_u32_e32 v42, vcc, 0x2420a000, v34
	s_nop 1
	v_addc_co_u32_e32 v43, vcc, 0, v35, vcc
	v_add_co_u32_e32 v44, vcc, 0x24210000, v34
	s_nop 1
	v_addc_co_u32_e32 v45, vcc, 0, v35, vcc
	v_add_co_u32_e32 v46, vcc, 0x24212000, v34
	s_nop 1
	v_addc_co_u32_e32 v47, vcc, 0, v35, vcc
	v_add_co_u32_e32 v48, vcc, 0x24218000, v34
	s_nop 1
	v_addc_co_u32_e32 v49, vcc, 0, v35, vcc
	v_add_co_u32_e32 v50, vcc, 0x2421a000, v34
	s_nop 1
	v_addc_co_u32_e32 v51, vcc, 0, v35, vcc
	global_load_dword v114, v[36:37], off
	global_load_dword v115, v[38:39], off
	global_load_dword v116, v[40:41], off
	global_load_dword v117, v[42:43], off
	global_load_dword v118, v[44:45], off
	global_load_dword v119, v[46:47], off
	global_load_dword v120, v[48:49], off
	global_load_dword v121, v[50:51], off
	v_add_co_u32_e32 v36, vcc, 0x24220000, v34
	s_nop 1
	v_addc_co_u32_e32 v37, vcc, 0, v35, vcc
	v_add_co_u32_e32 v38, vcc, 0x24222000, v34
	s_nop 1
	v_addc_co_u32_e32 v39, vcc, 0, v35, vcc
	v_add_co_u32_e32 v40, vcc, 0x24228000, v34
	s_nop 1
	v_addc_co_u32_e32 v41, vcc, 0, v35, vcc
	v_add_co_u32_e32 v42, vcc, 0x2422a000, v34
	s_nop 1
	v_addc_co_u32_e32 v43, vcc, 0, v35, vcc
	v_add_co_u32_e32 v44, vcc, 0x24230000, v34
	s_nop 1
	v_addc_co_u32_e32 v45, vcc, 0, v35, vcc
	v_add_co_u32_e32 v46, vcc, 0x24232000, v34
	s_nop 1
	v_addc_co_u32_e32 v47, vcc, 0, v35, vcc
	v_add_co_u32_e32 v48, vcc, 0x24238000, v34
	s_nop 1
	v_addc_co_u32_e32 v49, vcc, 0, v35, vcc
	v_add_co_u32_e32 v34, vcc, 0x2423a000, v34
	s_nop 1
	v_addc_co_u32_e32 v35, vcc, 0, v35, vcc
	global_load_dword v128, v[36:37], off
	global_load_dword v130, v[38:39], off
	global_load_dword v132, v[40:41], off
	global_load_dword v134, v[42:43], off
	global_load_dword v136, v[44:45], off
	global_load_dword v138, v[46:47], off
	global_load_dword v140, v[48:49], off
	global_load_dword v142, v[34:35], off
	v_lshl_add_u64 v[34:35], v[110:111], 0, s[72:73]
	v_add_co_u32_e32 v36, vcc, 0x24204000, v34
	s_nop 1
	v_addc_co_u32_e32 v37, vcc, 0, v35, vcc
	v_add_co_u32_e32 v34, vcc, 0x24304000, v34
	s_nop 1
	v_addc_co_u32_e32 v35, vcc, 0, v35, vcc
	global_load_dwordx4 v[50:53], v[36:37], off
	global_load_dwordx4 v[54:57], v[34:35], off
; __device__ __forceinline__ void hg_mfma(Frame& F, bf16* Y, int u, unsigned* prog = nullptr) {
;     ...
;         f32x16 o = f32x16{};
;         {
;           f32x16 pd; hg_qkt1(pd, (const char*)lds + HG_K, 32 * tb, qr, r32, hi);
; #pragma unroll
;           for (int r = 0; r < 16; ++r) { const int cr = (r & 3) + 8 * (r >> 2) + 4 * hi; pd[r] = (cr > r32) ? 0.f : pd[r]; }
;           bf16x8 pa0, pa1, pa2, pa3;
;           if (tb == 0) { PK4(pd, 0, pa0); PK4(pd, 8, pa1); hg_pv_half(o, vbV + vb * 512, pa0, pa1); }
;           else { f32x16 pf; hg_qkt1(pf, (const char*)lds + HG_K, 0, qr, r32, hi);
; #pragma unroll
;             for (int r = 0; r < 16; ++r) pf[r] = __builtin_fmaxf(pf[r], -3.0e38f);
;             PK4(pf, 0, pa0); PK4(pf, 8, pa1); PK4(pd, 0, pa2); PK4(pd, 8, pa3); pv_one<0>(o, vbV + vb * 512, pa0, pa1, pa2, pa3); }
.LBB0_1789:
	v_add_u32_e32 v34, v126, v125
	s_waitcnt lgkmcnt(0)
	s_barrier
	ds_read_b128 v[34:37], v34 offset:16384
	ds_read_b128 v[90:93], v160
	ds_read_b128 v[82:85], v161
	v_add_u32_e32 v38, v127, v125
	ds_read_b128 v[58:61], v38 offset:16384
	s_waitcnt lgkmcnt(2)
	v_mfma_f32_32x32x16_bf16 v[34:49], v[34:37], v[90:93], 0
	v_add_u32_e32 v62, v129, v125
	v_lshl_add_u64 v[204:205], v[108:109], 0, s[72:73]
	s_mov_b32 s58, 0x24006000
	s_mov_b64 s[52:53], 0x24006000
	v_add_u32_e32 v206, v139, v125
	s_waitcnt lgkmcnt(0)
	v_mfma_f32_32x32x16_bf16 v[34:49], v[58:61], v[82:85], v[34:49]
	ds_read_b128 v[58:61], v62 offset:16384
	ds_read_b128 v[94:97], v162
	ds_read_b128 v[78:81], v163
	v_add_u32_e32 v62, v131, v125
	ds_read_b128 v[62:65], v62 offset:16384
	s_waitcnt lgkmcnt(2)
	v_mfma_f32_32x32x16_bf16 v[34:49], v[58:61], v[94:97], v[34:49]
	v_add_u32_e32 v58, v133, v125
	ds_read_b128 v[58:61], v58 offset:16384
	ds_read_b128 v[86:89], v164
	ds_read_b128 v[70:73], v165
	s_waitcnt lgkmcnt(3)
	v_mfma_f32_32x32x16_bf16 v[34:49], v[62:65], v[78:81], v[34:49]
	v_add_u32_e32 v62, v135, v125
	ds_read_b128 v[62:65], v62 offset:16384
	ds_read_b128 v[74:77], v166
	ds_read_b128 v[66:69], v167
	s_waitcnt lgkmcnt(4)
	v_mfma_f32_32x32x16_bf16 v[34:49], v[58:61], v[86:89], v[34:49]
	v_add_u32_e32 v58, v137, v125
	ds_read_b128 v[58:61], v58 offset:16384
	s_waitcnt lgkmcnt(3)
	v_mfma_f32_32x32x16_bf16 v[34:49], v[62:65], v[70:73], v[34:49]
	ds_read_b128 v[204:207], v206 offset:16384
	s_mov_b64 s[52:53], -1
	s_waitcnt lgkmcnt(1)
	v_mfma_f32_32x32x16_bf16 v[34:49], v[58:61], v[74:77], v[34:49]
	s_and_b64 vcc, exec, s[64:65]
	s_waitcnt lgkmcnt(0)
	v_mfma_f32_32x32x16_bf16 v[34:49], v[204:207], v[66:69], v[34:49]
	s_nop 11
	v_cndmask_b32_e64 v218, v34, 0, s[18:19]
	v_cndmask_b32_e64 v220, 0, v35, s[20:21]
	v_cndmask_b32_e64 v215, v36, 0, s[22:23]
	v_cndmask_b32_e64 v219, v37, 0, s[24:25]
	v_cndmask_b32_e64 v213, v38, 0, s[26:27]
	v_cndmask_b32_e64 v217, v39, 0, s[28:29]
	v_cndmask_b32_e64 v212, v40, 0, s[30:31]
	v_cndmask_b32_e64 v214, v41, 0, s[34:35]
	v_cndmask_b32_e64 v209, v42, 0, s[36:37]
	v_cndmask_b32_e64 v211, v43, 0, s[38:39]
	v_cndmask_b32_e64 v207, v44, 0, s[40:41]
	v_cndmask_b32_e64 v210, v45, 0, s[42:43]
	v_cndmask_b32_e64 v205, v46, 0, s[44:45]
	v_cndmask_b32_e64 v208, v47, 0, s[46:47]
	v_cndmask_b32_e64 v204, v48, 0, s[48:49]
	v_cndmask_b32_e64 v206, v49, 0, s[50:51]
	s_cbranch_vccz .LBB0_1791
	v_add_u32_e32 v34, v126, v124
	ds_read_b128 v[34:37], v34 offset:16384
	v_add_u32_e32 v38, v127, v124
	ds_read_b128 v[222:225], v38 offset:16384
	v_add_u32_e32 v221, v129, v124
	s_waitcnt lgkmcnt(1)
	v_mfma_f32_32x32x16_bf16 v[34:49], v[34:37], v[90:93], 0
	s_waitcnt lgkmcnt(0)
	v_mfma_f32_32x32x16_bf16 v[34:49], v[222:225], v[82:85], v[34:49]
	ds_read_b128 v[222:225], v221 offset:16384
	v_add_u32_e32 v221, v131, v124
	ds_read_b128 v[226:229], v221 offset:16384
	v_add_u32_e32 v221, v133, v124
	s_waitcnt lgkmcnt(1)
	v_mfma_f32_32x32x16_bf16 v[34:49], v[222:225], v[94:97], v[34:49]
	ds_read_b128 v[222:225], v221 offset:16384
	v_add_u32_e32 v221, v135, v124
	s_waitcnt lgkmcnt(1)
	v_mfma_f32_32x32x16_bf16 v[34:49], v[226:229], v[78:81], v[34:49]
	ds_read_b128 v[226:229], v221 offset:16384
	v_add_u32_e32 v221, v137, v124
	s_waitcnt lgkmcnt(1)
	v_mfma_f32_32x32x16_bf16 v[34:49], v[222:225], v[86:89], v[34:49]
	ds_read_b128 v[222:225], v221 offset:16384
	v_add_u32_e32 v221, v139, v124
	s_waitcnt lgkmcnt(1)
	v_mfma_f32_32x32x16_bf16 v[34:49], v[226:229], v[70:73], v[34:49]
	ds_read_b128 v[226:229], v221 offset:16384
	s_waitcnt lgkmcnt(1)
	v_mfma_f32_32x32x16_bf16 v[34:49], v[222:225], v[74:77], v[34:49]
	s_waitcnt lgkmcnt(0)
	v_mfma_f32_32x32x16_bf16 v[34:49], v[226:229], v[66:69], v[34:49]
	s_nop 11
	v_max_f32_e32 v34, v34, v34
	v_max_f32_e32 v35, v35, v35
	v_max_f32_e32 v36, v36, v36
	v_max_f32_e32 v37, v37, v37
	v_max_f32_e32 v38, v38, v38
	v_max_f32_e32 v39, v39, v39
	v_max_f32_e32 v40, v40, v40
	v_max_f32_e32 v41, v41, v41
	v_max_f32_e32 v42, v42, v42
	v_max_f32_e32 v43, v43, v43
	v_max_f32_e32 v44, v44, v44
	v_max_f32_e32 v45, v45, v45
	v_max_f32_e32 v46, v46, v46
	v_max_f32_e32 v47, v47, v47
	v_max_f32_e32 v48, v48, v48
	v_max_f32_e32 v49, v49, v49
	v_max_f32_e32 v34, 0xff61b1e6, v34
	v_max_f32_e32 v35, 0xff61b1e6, v35
	v_max_f32_e32 v36, 0xff61b1e6, v36
	v_max_f32_e32 v37, 0xff61b1e6, v37
	v_max_f32_e32 v38, 0xff61b1e6, v38
	v_max_f32_e32 v39, 0xff61b1e6, v39
	v_max_f32_e32 v40, 0xff61b1e6, v40
	v_max_f32_e32 v41, 0xff61b1e6, v41
	v_max_f32_e32 v42, 0xff61b1e6, v42
	v_max_f32_e32 v43, 0xff61b1e6, v43
	v_max_f32_e32 v44, 0xff61b1e6, v44
	v_max_f32_e32 v45, 0xff61b1e6, v45
	v_max_f32_e32 v46, 0xff61b1e6, v46
	v_max_f32_e32 v47, 0xff61b1e6, v47
	v_max_f32_e32 v48, 0xff61b1e6, v48
	v_max_f32_e32 v49, 0xff61b1e6, v49
	v_cvt_pk_bf16_f32 v34, v34, v35
	v_cvt_pk_bf16_f32 v35, v36, v37
	v_cvt_pk_bf16_f32 v36, v38, v39
	v_cvt_pk_bf16_f32 v37, v40, v41
	v_cvt_pk_bf16_f32 v222, v42, v43
	v_cvt_pk_bf16_f32 v223, v44, v45
	v_cvt_pk_bf16_f32 v224, v46, v47
	v_cvt_pk_bf16_f32 v225, v48, v49
	v_cvt_pk_bf16_f32 v226, v218, v220
	v_cvt_pk_bf16_f32 v227, v215, v219
	v_cvt_pk_bf16_f32 v228, v213, v217
	v_cvt_pk_bf16_f32 v229, v212, v214
	v_cvt_pk_bf16_f32 v230, v209, v211
	v_cvt_pk_bf16_f32 v231, v207, v210
	v_cvt_pk_bf16_f32 v232, v205, v208
	v_cvt_pk_bf16_f32 v233, v204, v206
	ds_read_b64_tr_b16 v[38:39], v141 offset:0
	ds_read_b64_tr_b16 v[40:41], v141 offset:0x800
	ds_read_b64_tr_b16 v[234:235], v141 offset:0x1000
	ds_read_b64_tr_b16 v[236:237], v141 offset:0x1800
	ds_read_b64_tr_b16 v[238:239], v141 offset:0x2000
	ds_read_b64_tr_b16 v[240:241], v141 offset:0x2800
	ds_read_b64_tr_b16 v[242:243], v141 offset:0x3000
	ds_read_b64_tr_b16 v[244:245], v141 offset:0x3800
	s_waitcnt lgkmcnt(0)
	s_nop 0
	v_permlane32_swap_b32_e32 v34, v36
	v_permlane32_swap_b32_e32 v35, v37
	v_permlane32_swap_b32_e32 v222, v224
	v_permlane32_swap_b32_e32 v223, v225
	v_permlane32_swap_b32_e32 v226, v228
	v_permlane32_swap_b32_e32 v227, v229
	v_permlane32_swap_b32_e32 v230, v232
	v_permlane32_swap_b32_e32 v231, v233
	v_mfma_f32_32x32x16_bf16 v[34:49], v[34:37], v[38:41], 0
	s_mov_b64 s[52:53], 0
	v_mfma_f32_32x32x16_bf16 v[34:49], v[222:225], v[234:237], v[34:49]
	v_mfma_f32_32x32x16_bf16 v[34:49], v[226:229], v[238:241], v[34:49]
	v_mfma_f32_32x32x16_bf16 v[34:49], v[230:233], v[242:245], v[34:49]

; __device__ __forceinline__ void hg_mfma(Frame& F, bf16* Y, int u, unsigned* prog = nullptr) {
;     ...
;       if (c + 1 < SEQ / 64) HG_LOAD(c + 1);
;       __syncthreads();
;       { const size_t row_ = row0 + (size_t)c * 64 + (tid >> 3); ga = *(const v4u*)(proj + row_ * HG_NP + 12288 + hd * 128 + (tid & 7) * 16); gb = *(const v4u*)(proj + row_ * HG_NP + 12288 + hd * 128 + (tid & 7) * 16 + 8); }
.Lmy_hg_last:
	s_waitcnt vmcnt(0)
	s_branch .LBB0_1789
